# combo32 + dead per-XCD release add removed from the leader path (members poll the global flag), leader no longer waits for its acknowledgement
# speedup vs baseline: 1.0027x; 1.0027x over previous
; __device__ __forceinline__ unsigned xb_ld(unsigned* p)              { return __hip_atomic_load(p, __ATOMIC_RELAXED, __HIP_MEMORY_SCOPE_AGENT); }
; __device__ __forceinline__ unsigned xb_add(unsigned* p, unsigned v) { return __hip_atomic_fetch_add(p, v, __ATOMIC_RELAXED, __HIP_MEMORY_SCOPE_AGENT); }
; #define XB_SPIN(cond, bar) do { unsigned _sp = 0; while (cond) { __builtin_amdgcn_s_sleep(1); \
;     if ((++_sp & 255u) == 0u) { if (xb_ld(&(bar)[XB_TMO])) break; if (_sp > XB_SPIN_CAP) { atomicAdd(&(bar)[XB_TMO], 1u); break; } } } } while (0)
; __device__ __forceinline__ void xcd_barrier(const XcdBarrier& b, const bool xb_is_leader) {
;     ...
;             if (og + 1u == (tg + 1u) * nx) xb_add(&bar[XB_TOPGEN], 1u);
;             else XB_SPIN(xb_ld(&bar[XB_TOPGEN]) == tg, bar);
;             __builtin_amdgcn_fence(__ATOMIC_ACQUIRE, "agent");
;             xb_add(&bar[XB_XGEN(b.x)], 1u);
;             asm volatile("s_waitcnt vmcnt(0)" ::: "memory");
.LBB0_235:
	s_or_b64 exec, exec, s[0:1]
	s_mov_b64 s[0:1], exec
	v_mbcnt_lo_u32_b32 v0, s0, 0
	v_mbcnt_hi_u32_b32 v0, s1, v0
	v_cmp_eq_u32_e32 vcc, 0, v0
	s_waitcnt vmcnt(0)
	buffer_inv sc1
	s_and_saveexec_b64 s[8:9], vcc
	s_cbranch_execz .LBB0_237
	s_bcnt1_i32_b64 s0, s[0:1]
	v_mov_b32_e32 v0, 0x2000
	v_mov_b32_e32 v1, s0
.LBB0_237:
	s_or_b64 exec, exec, s[8:9]
	s_waitcnt vmcnt(0)

; __device__ __forceinline__ unsigned xb_ld(unsigned* p)              { return __hip_atomic_load(p, __ATOMIC_RELAXED, __HIP_MEMORY_SCOPE_AGENT); }
; __device__ __forceinline__ unsigned xb_add(unsigned* p, unsigned v) { return __hip_atomic_fetch_add(p, v, __ATOMIC_RELAXED, __HIP_MEMORY_SCOPE_AGENT); }
; #define XB_SPIN(cond, bar) do { unsigned _sp = 0; while (cond) { __builtin_amdgcn_s_sleep(1); \
;     if ((++_sp & 255u) == 0u) { if (xb_ld(&(bar)[XB_TMO])) break; if (_sp > XB_SPIN_CAP) { atomicAdd(&(bar)[XB_TMO], 1u); break; } } } } while (0)
; __device__ __forceinline__ void xcd_barrier(const XcdBarrier& b, const bool xb_is_leader) {
;     ...
;             if (og + 1u == (tg + 1u) * nx) xb_add(&bar[XB_TOPGEN], 1u);
;             else XB_SPIN(xb_ld(&bar[XB_TOPGEN]) == tg, bar);
;             __builtin_amdgcn_fence(__ATOMIC_ACQUIRE, "agent");
;             xb_add(&bar[XB_XGEN(b.x)], 1u);
;             asm volatile("s_waitcnt vmcnt(0)" ::: "memory");
.LBB0_342:
	s_or_b64 exec, exec, s[0:1]
	s_mov_b64 s[0:1], exec
	v_mbcnt_lo_u32_b32 v0, s0, 0
	v_mbcnt_hi_u32_b32 v0, s1, v0
	v_cmp_eq_u32_e32 vcc, 0, v0
	s_waitcnt vmcnt(0)
	buffer_inv sc1
	s_and_saveexec_b64 s[8:9], vcc
	s_cbranch_execz .LBB0_344
	s_bcnt1_i32_b64 s0, s[0:1]
	v_mov_b32_e32 v0, 0x2000
	v_mov_b32_e32 v1, s0
.LBB0_344:
	s_or_b64 exec, exec, s[8:9]
	s_waitcnt vmcnt(0)

; __device__ __forceinline__ unsigned xb_ld(unsigned* p)              { return __hip_atomic_load(p, __ATOMIC_RELAXED, __HIP_MEMORY_SCOPE_AGENT); }
; __device__ __forceinline__ unsigned xb_add(unsigned* p, unsigned v) { return __hip_atomic_fetch_add(p, v, __ATOMIC_RELAXED, __HIP_MEMORY_SCOPE_AGENT); }
; #define XB_SPIN(cond, bar) do { unsigned _sp = 0; while (cond) { __builtin_amdgcn_s_sleep(1); \
;     if ((++_sp & 255u) == 0u) { if (xb_ld(&(bar)[XB_TMO])) break; if (_sp > XB_SPIN_CAP) { atomicAdd(&(bar)[XB_TMO], 1u); break; } } } } while (0)
; __device__ __forceinline__ void xcd_barrier(const XcdBarrier& b, const bool xb_is_leader) {
;     ...
;             if (og + 1u == (tg + 1u) * nx) xb_add(&bar[XB_TOPGEN], 1u);
;             else XB_SPIN(xb_ld(&bar[XB_TOPGEN]) == tg, bar);
;             __builtin_amdgcn_fence(__ATOMIC_ACQUIRE, "agent");
;             xb_add(&bar[XB_XGEN(b.x)], 1u);
;             asm volatile("s_waitcnt vmcnt(0)" ::: "memory");
.LBB0_511:
	s_or_b64 exec, exec, s[0:1]
	s_mov_b64 s[0:1], exec
	v_mbcnt_lo_u32_b32 v0, s0, 0
	v_mbcnt_hi_u32_b32 v0, s1, v0
	v_cmp_eq_u32_e32 vcc, 0, v0
	s_waitcnt vmcnt(0)
	buffer_inv sc1
	s_and_saveexec_b64 s[8:9], vcc
	s_cbranch_execz .LBB0_513
	s_bcnt1_i32_b64 s0, s[0:1]
	v_mov_b32_e32 v0, 0x2000
	v_mov_b32_e32 v1, s0
.LBB0_513:
	s_or_b64 exec, exec, s[8:9]
	s_waitcnt vmcnt(0)

; __device__ __forceinline__ unsigned xb_ld(unsigned* p)              { return __hip_atomic_load(p, __ATOMIC_RELAXED, __HIP_MEMORY_SCOPE_AGENT); }
; __device__ __forceinline__ unsigned xb_add(unsigned* p, unsigned v) { return __hip_atomic_fetch_add(p, v, __ATOMIC_RELAXED, __HIP_MEMORY_SCOPE_AGENT); }
; #define XB_SPIN(cond, bar) do { unsigned _sp = 0; while (cond) { __builtin_amdgcn_s_sleep(1); \
;     if ((++_sp & 255u) == 0u) { if (xb_ld(&(bar)[XB_TMO])) break; if (_sp > XB_SPIN_CAP) { atomicAdd(&(bar)[XB_TMO], 1u); break; } } } } while (0)
; __device__ __forceinline__ void xcd_barrier(const XcdBarrier& b, const bool xb_is_leader) {
;     ...
;             if (og + 1u == (tg + 1u) * nx) xb_add(&bar[XB_TOPGEN], 1u);
;             else XB_SPIN(xb_ld(&bar[XB_TOPGEN]) == tg, bar);
;             __builtin_amdgcn_fence(__ATOMIC_ACQUIRE, "agent");
;             xb_add(&bar[XB_XGEN(b.x)], 1u);
;             asm volatile("s_waitcnt vmcnt(0)" ::: "memory");
.LBB0_671:
	s_or_b64 exec, exec, s[0:1]
	s_mov_b64 s[0:1], exec
	v_mbcnt_lo_u32_b32 v0, s0, 0
	v_mbcnt_hi_u32_b32 v0, s1, v0
	v_cmp_eq_u32_e32 vcc, 0, v0
	s_waitcnt vmcnt(0)
	buffer_inv sc1
	s_and_saveexec_b64 s[8:9], vcc
	s_cbranch_execz .LBB0_673
	s_bcnt1_i32_b64 s0, s[0:1]
	v_mov_b32_e32 v0, 0x2000
	v_mov_b32_e32 v1, s0
.LBB0_673:
	s_or_b64 exec, exec, s[8:9]
	s_waitcnt vmcnt(0)

; __device__ __forceinline__ unsigned xb_ld(unsigned* p)              { return __hip_atomic_load(p, __ATOMIC_RELAXED, __HIP_MEMORY_SCOPE_AGENT); }
; __device__ __forceinline__ unsigned xb_add(unsigned* p, unsigned v) { return __hip_atomic_fetch_add(p, v, __ATOMIC_RELAXED, __HIP_MEMORY_SCOPE_AGENT); }
; #define XB_SPIN(cond, bar) do { unsigned _sp = 0; while (cond) { __builtin_amdgcn_s_sleep(1); \
;     if ((++_sp & 255u) == 0u) { if (xb_ld(&(bar)[XB_TMO])) break; if (_sp > XB_SPIN_CAP) { atomicAdd(&(bar)[XB_TMO], 1u); break; } } } } while (0)
; __device__ __forceinline__ void xcd_barrier(const XcdBarrier& b, const bool xb_is_leader) {
;     ...
;             if (og + 1u == (tg + 1u) * nx) xb_add(&bar[XB_TOPGEN], 1u);
;             else XB_SPIN(xb_ld(&bar[XB_TOPGEN]) == tg, bar);
;             __builtin_amdgcn_fence(__ATOMIC_ACQUIRE, "agent");
;             xb_add(&bar[XB_XGEN(b.x)], 1u);
;             asm volatile("s_waitcnt vmcnt(0)" ::: "memory");
.LBB0_780:
	s_or_b64 exec, exec, s[0:1]
	s_mov_b64 s[0:1], exec
	v_mbcnt_lo_u32_b32 v0, s0, 0
	v_mbcnt_hi_u32_b32 v0, s1, v0
	v_cmp_eq_u32_e32 vcc, 0, v0
	s_waitcnt vmcnt(0)
	buffer_inv sc1
	s_and_saveexec_b64 s[8:9], vcc
	s_cbranch_execz .LBB0_782
	s_bcnt1_i32_b64 s0, s[0:1]
	v_mov_b32_e32 v0, 0x2000
	v_mov_b32_e32 v1, s0
.LBB0_782:
	s_or_b64 exec, exec, s[8:9]
	s_waitcnt vmcnt(0)

; __device__ __forceinline__ unsigned xb_ld(unsigned* p)              { return __hip_atomic_load(p, __ATOMIC_RELAXED, __HIP_MEMORY_SCOPE_AGENT); }
; __device__ __forceinline__ unsigned xb_add(unsigned* p, unsigned v) { return __hip_atomic_fetch_add(p, v, __ATOMIC_RELAXED, __HIP_MEMORY_SCOPE_AGENT); }
; #define XB_SPIN(cond, bar) do { unsigned _sp = 0; while (cond) { __builtin_amdgcn_s_sleep(1); \
;     if ((++_sp & 255u) == 0u) { if (xb_ld(&(bar)[XB_TMO])) break; if (_sp > XB_SPIN_CAP) { atomicAdd(&(bar)[XB_TMO], 1u); break; } } } } while (0)
; __device__ __forceinline__ void xcd_barrier(const XcdBarrier& b, const bool xb_is_leader) {
;     ...
;             if (og + 1u == (tg + 1u) * nx) xb_add(&bar[XB_TOPGEN], 1u);
;             else XB_SPIN(xb_ld(&bar[XB_TOPGEN]) == tg, bar);
;             __builtin_amdgcn_fence(__ATOMIC_ACQUIRE, "agent");
;             xb_add(&bar[XB_XGEN(b.x)], 1u);
;             asm volatile("s_waitcnt vmcnt(0)" ::: "memory");
.LBB0_945:
	s_or_b64 exec, exec, s[0:1]
	s_mov_b64 s[0:1], exec
	v_mbcnt_lo_u32_b32 v0, s0, 0
	v_mbcnt_hi_u32_b32 v0, s1, v0
	v_cmp_eq_u32_e32 vcc, 0, v0
	s_waitcnt vmcnt(0)
	buffer_inv sc1
	s_and_saveexec_b64 s[8:9], vcc
	s_cbranch_execz .LBB0_947
	s_bcnt1_i32_b64 s0, s[0:1]
	v_mov_b32_e32 v0, 0x2000
	v_mov_b32_e32 v1, s0
.LBB0_947:
	s_or_b64 exec, exec, s[8:9]
	s_waitcnt vmcnt(0)

; __device__ __forceinline__ unsigned xb_ld(unsigned* p)              { return __hip_atomic_load(p, __ATOMIC_RELAXED, __HIP_MEMORY_SCOPE_AGENT); }
; __device__ __forceinline__ unsigned xb_add(unsigned* p, unsigned v) { return __hip_atomic_fetch_add(p, v, __ATOMIC_RELAXED, __HIP_MEMORY_SCOPE_AGENT); }
; #define XB_SPIN(cond, bar) do { unsigned _sp = 0; while (cond) { __builtin_amdgcn_s_sleep(1); \
;     if ((++_sp & 255u) == 0u) { if (xb_ld(&(bar)[XB_TMO])) break; if (_sp > XB_SPIN_CAP) { atomicAdd(&(bar)[XB_TMO], 1u); break; } } } } while (0)
; __device__ __forceinline__ void xcd_barrier(const XcdBarrier& b, const bool xb_is_leader) {
;     ...
;             if (og + 1u == (tg + 1u) * nx) xb_add(&bar[XB_TOPGEN], 1u);
;             else XB_SPIN(xb_ld(&bar[XB_TOPGEN]) == tg, bar);
;             __builtin_amdgcn_fence(__ATOMIC_ACQUIRE, "agent");
;             xb_add(&bar[XB_XGEN(b.x)], 1u);
;             asm volatile("s_waitcnt vmcnt(0)" ::: "memory");
.LBB0_1021:
	s_or_b64 exec, exec, s[0:1]
	s_mov_b64 s[0:1], exec
	v_mbcnt_lo_u32_b32 v0, s0, 0
	v_mbcnt_hi_u32_b32 v0, s1, v0
	v_cmp_eq_u32_e32 vcc, 0, v0
	s_waitcnt vmcnt(0)
	buffer_inv sc1
	s_and_saveexec_b64 s[8:9], vcc
	s_cbranch_execz .LBB0_1023
	s_bcnt1_i32_b64 s0, s[0:1]
	v_mov_b32_e32 v0, 0x2000
	v_mov_b32_e32 v1, s0
.LBB0_1023:
	s_or_b64 exec, exec, s[8:9]
	s_waitcnt vmcnt(0)

; __device__ __forceinline__ unsigned xb_ld(unsigned* p)              { return __hip_atomic_load(p, __ATOMIC_RELAXED, __HIP_MEMORY_SCOPE_AGENT); }
; __device__ __forceinline__ unsigned xb_add(unsigned* p, unsigned v) { return __hip_atomic_fetch_add(p, v, __ATOMIC_RELAXED, __HIP_MEMORY_SCOPE_AGENT); }
; #define XB_SPIN(cond, bar) do { unsigned _sp = 0; while (cond) { __builtin_amdgcn_s_sleep(1); \
;     if ((++_sp & 255u) == 0u) { if (xb_ld(&(bar)[XB_TMO])) break; if (_sp > XB_SPIN_CAP) { atomicAdd(&(bar)[XB_TMO], 1u); break; } } } } while (0)
; __device__ __forceinline__ void xcd_barrier(const XcdBarrier& b, const bool xb_is_leader) {
;     ...
;             if (og + 1u == (tg + 1u) * nx) xb_add(&bar[XB_TOPGEN], 1u);
;             else XB_SPIN(xb_ld(&bar[XB_TOPGEN]) == tg, bar);
;             __builtin_amdgcn_fence(__ATOMIC_ACQUIRE, "agent");
;             xb_add(&bar[XB_XGEN(b.x)], 1u);
;             asm volatile("s_waitcnt vmcnt(0)" ::: "memory");
.LBB0_1102:
	s_or_b64 exec, exec, s[0:1]
	s_mov_b64 s[0:1], exec
	v_mbcnt_lo_u32_b32 v0, s0, 0
	v_mbcnt_hi_u32_b32 v0, s1, v0
	v_cmp_eq_u32_e32 vcc, 0, v0
	s_waitcnt vmcnt(0)
	buffer_inv sc1
	s_and_saveexec_b64 s[8:9], vcc
	s_cbranch_execz .LBB0_1104
	s_bcnt1_i32_b64 s0, s[0:1]
	v_mov_b32_e32 v0, 0x2000
	v_mov_b32_e32 v1, s0
.LBB0_1104:
	s_or_b64 exec, exec, s[8:9]
	s_waitcnt vmcnt(0)

; __device__ __forceinline__ unsigned xb_ld(unsigned* p)              { return __hip_atomic_load(p, __ATOMIC_RELAXED, __HIP_MEMORY_SCOPE_AGENT); }
; __device__ __forceinline__ unsigned xb_add(unsigned* p, unsigned v) { return __hip_atomic_fetch_add(p, v, __ATOMIC_RELAXED, __HIP_MEMORY_SCOPE_AGENT); }
; #define XB_SPIN(cond, bar) do { unsigned _sp = 0; while (cond) { __builtin_amdgcn_s_sleep(1); \
;     if ((++_sp & 255u) == 0u) { if (xb_ld(&(bar)[XB_TMO])) break; if (_sp > XB_SPIN_CAP) { atomicAdd(&(bar)[XB_TMO], 1u); break; } } } } while (0)
; __device__ __forceinline__ void xcd_barrier(const XcdBarrier& b, const bool xb_is_leader) {
;     ...
;             if (og + 1u == (tg + 1u) * nx) xb_add(&bar[XB_TOPGEN], 1u);
;             else XB_SPIN(xb_ld(&bar[XB_TOPGEN]) == tg, bar);
;             __builtin_amdgcn_fence(__ATOMIC_ACQUIRE, "agent");
;             xb_add(&bar[XB_XGEN(b.x)], 1u);
;             asm volatile("s_waitcnt vmcnt(0)" ::: "memory");
.LBB0_1161:
	s_or_b64 exec, exec, s[0:1]
	s_mov_b64 s[0:1], exec
	v_mbcnt_lo_u32_b32 v0, s0, 0
	v_mbcnt_hi_u32_b32 v0, s1, v0
	v_cmp_eq_u32_e32 vcc, 0, v0
	s_waitcnt vmcnt(0)
	buffer_inv sc1
	s_and_saveexec_b64 s[8:9], vcc
	s_cbranch_execz .LBB0_1163
	s_bcnt1_i32_b64 s0, s[0:1]
	v_mov_b32_e32 v0, 0x2000
	v_mov_b32_e32 v1, s0
.LBB0_1163:
	s_or_b64 exec, exec, s[8:9]
	s_waitcnt vmcnt(0)

; __device__ __forceinline__ unsigned xb_ld(unsigned* p)              { return __hip_atomic_load(p, __ATOMIC_RELAXED, __HIP_MEMORY_SCOPE_AGENT); }
; __device__ __forceinline__ unsigned xb_add(unsigned* p, unsigned v) { return __hip_atomic_fetch_add(p, v, __ATOMIC_RELAXED, __HIP_MEMORY_SCOPE_AGENT); }
; #define XB_SPIN(cond, bar) do { unsigned _sp = 0; while (cond) { __builtin_amdgcn_s_sleep(1); \
;     if ((++_sp & 255u) == 0u) { if (xb_ld(&(bar)[XB_TMO])) break; if (_sp > XB_SPIN_CAP) { atomicAdd(&(bar)[XB_TMO], 1u); break; } } } } while (0)
; __device__ __forceinline__ void xcd_barrier(const XcdBarrier& b, const bool xb_is_leader) {
;     ...
;             if (og + 1u == (tg + 1u) * nx) xb_add(&bar[XB_TOPGEN], 1u);
;             else XB_SPIN(xb_ld(&bar[XB_TOPGEN]) == tg, bar);
;             __builtin_amdgcn_fence(__ATOMIC_ACQUIRE, "agent");
;             xb_add(&bar[XB_XGEN(b.x)], 1u);
;             asm volatile("s_waitcnt vmcnt(0)" ::: "memory");
.LBB0_1268:
	s_or_b64 exec, exec, s[0:1]
	s_mov_b64 s[0:1], exec
	v_mbcnt_lo_u32_b32 v0, s0, 0
	v_mbcnt_hi_u32_b32 v0, s1, v0
	v_cmp_eq_u32_e32 vcc, 0, v0
	s_waitcnt vmcnt(0)
	buffer_inv sc1
	s_and_saveexec_b64 s[8:9], vcc
	s_cbranch_execz .LBB0_1270
	s_bcnt1_i32_b64 s0, s[0:1]
	v_mov_b32_e32 v0, 0x2000
	v_mov_b32_e32 v1, s0
.LBB0_1270:
	s_or_b64 exec, exec, s[8:9]
	s_waitcnt vmcnt(0)

; __device__ __forceinline__ unsigned xb_ld(unsigned* p)              { return __hip_atomic_load(p, __ATOMIC_RELAXED, __HIP_MEMORY_SCOPE_AGENT); }
; __device__ __forceinline__ unsigned xb_add(unsigned* p, unsigned v) { return __hip_atomic_fetch_add(p, v, __ATOMIC_RELAXED, __HIP_MEMORY_SCOPE_AGENT); }
; #define XB_SPIN(cond, bar) do { unsigned _sp = 0; while (cond) { __builtin_amdgcn_s_sleep(1); \
;     if ((++_sp & 255u) == 0u) { if (xb_ld(&(bar)[XB_TMO])) break; if (_sp > XB_SPIN_CAP) { atomicAdd(&(bar)[XB_TMO], 1u); break; } } } } while (0)
; __device__ __forceinline__ void xcd_barrier(const XcdBarrier& b, const bool xb_is_leader) {
;     ...
;             if (og + 1u == (tg + 1u) * nx) xb_add(&bar[XB_TOPGEN], 1u);
;             else XB_SPIN(xb_ld(&bar[XB_TOPGEN]) == tg, bar);
;             __builtin_amdgcn_fence(__ATOMIC_ACQUIRE, "agent");
;             xb_add(&bar[XB_XGEN(b.x)], 1u);
;             asm volatile("s_waitcnt vmcnt(0)" ::: "memory");
.LBB0_1437:
	s_or_b64 exec, exec, s[0:1]
	s_mov_b64 s[0:1], exec
	v_mbcnt_lo_u32_b32 v0, s0, 0
	v_mbcnt_hi_u32_b32 v0, s1, v0
	v_cmp_eq_u32_e32 vcc, 0, v0
	s_waitcnt vmcnt(0)
	buffer_inv sc1
	s_and_saveexec_b64 s[8:9], vcc
	s_cbranch_execz .LBB0_1439
	s_bcnt1_i32_b64 s0, s[0:1]
	v_mov_b32_e32 v0, 0x2000
	v_mov_b32_e32 v1, s0
.LBB0_1439:
	s_or_b64 exec, exec, s[8:9]
	s_waitcnt vmcnt(0)

; __device__ __forceinline__ unsigned xb_ld(unsigned* p)              { return __hip_atomic_load(p, __ATOMIC_RELAXED, __HIP_MEMORY_SCOPE_AGENT); }
; __device__ __forceinline__ unsigned xb_add(unsigned* p, unsigned v) { return __hip_atomic_fetch_add(p, v, __ATOMIC_RELAXED, __HIP_MEMORY_SCOPE_AGENT); }
; #define XB_SPIN(cond, bar) do { unsigned _sp = 0; while (cond) { __builtin_amdgcn_s_sleep(1); \
;     if ((++_sp & 255u) == 0u) { if (xb_ld(&(bar)[XB_TMO])) break; if (_sp > XB_SPIN_CAP) { atomicAdd(&(bar)[XB_TMO], 1u); break; } } } } while (0)
; __device__ __forceinline__ void xcd_barrier(const XcdBarrier& b, const bool xb_is_leader) {
;     ...
;             if (og + 1u == (tg + 1u) * nx) xb_add(&bar[XB_TOPGEN], 1u);
;             else XB_SPIN(xb_ld(&bar[XB_TOPGEN]) == tg, bar);
;             __builtin_amdgcn_fence(__ATOMIC_ACQUIRE, "agent");
;             xb_add(&bar[XB_XGEN(b.x)], 1u);
;             asm volatile("s_waitcnt vmcnt(0)" ::: "memory");
.LBB0_1533:
	s_or_b64 exec, exec, s[0:1]
	s_mov_b64 s[0:1], exec
	v_mbcnt_lo_u32_b32 v0, s0, 0
	v_mbcnt_hi_u32_b32 v0, s1, v0
	v_cmp_eq_u32_e32 vcc, 0, v0
	s_waitcnt vmcnt(0)
	buffer_inv sc1
	s_and_saveexec_b64 s[8:9], vcc
	s_cbranch_execz .LBB0_1535
	s_bcnt1_i32_b64 s0, s[0:1]
	v_mov_b32_e32 v0, 0x2000
	v_mov_b32_e32 v1, s0
.LBB0_1535:
	s_or_b64 exec, exec, s[8:9]
	s_waitcnt vmcnt(0)

; __device__ __forceinline__ unsigned xb_ld(unsigned* p)              { return __hip_atomic_load(p, __ATOMIC_RELAXED, __HIP_MEMORY_SCOPE_AGENT); }
; __device__ __forceinline__ unsigned xb_add(unsigned* p, unsigned v) { return __hip_atomic_fetch_add(p, v, __ATOMIC_RELAXED, __HIP_MEMORY_SCOPE_AGENT); }
; #define XB_SPIN(cond, bar) do { unsigned _sp = 0; while (cond) { __builtin_amdgcn_s_sleep(1); \
;     if ((++_sp & 255u) == 0u) { if (xb_ld(&(bar)[XB_TMO])) break; if (_sp > XB_SPIN_CAP) { atomicAdd(&(bar)[XB_TMO], 1u); break; } } } } while (0)
; __device__ __forceinline__ void xcd_barrier(const XcdBarrier& b, const bool xb_is_leader) {
;     ...
;             if (og + 1u == (tg + 1u) * nx) xb_add(&bar[XB_TOPGEN], 1u);
;             else XB_SPIN(xb_ld(&bar[XB_TOPGEN]) == tg, bar);
;             __builtin_amdgcn_fence(__ATOMIC_ACQUIRE, "agent");
;             xb_add(&bar[XB_XGEN(b.x)], 1u);
;             asm volatile("s_waitcnt vmcnt(0)" ::: "memory");
.LBB0_1642:
	s_or_b64 exec, exec, s[0:1]
	s_mov_b64 s[0:1], exec
	v_mbcnt_lo_u32_b32 v0, s0, 0
	v_mbcnt_hi_u32_b32 v0, s1, v0
	v_cmp_eq_u32_e32 vcc, 0, v0
	s_waitcnt vmcnt(0)
	buffer_inv sc1
	s_and_saveexec_b64 s[8:9], vcc
	s_cbranch_execz .LBB0_1644
	s_bcnt1_i32_b64 s0, s[0:1]
	v_mov_b32_e32 v0, 0x2000
	v_mov_b32_e32 v1, s0
.LBB0_1644:
	s_or_b64 exec, exec, s[8:9]
	s_waitcnt vmcnt(0)

; __device__ __forceinline__ unsigned xb_ld(unsigned* p)              { return __hip_atomic_load(p, __ATOMIC_RELAXED, __HIP_MEMORY_SCOPE_AGENT); }
; __device__ __forceinline__ unsigned xb_add(unsigned* p, unsigned v) { return __hip_atomic_fetch_add(p, v, __ATOMIC_RELAXED, __HIP_MEMORY_SCOPE_AGENT); }
; #define XB_SPIN(cond, bar) do { unsigned _sp = 0; while (cond) { __builtin_amdgcn_s_sleep(1); \
;     if ((++_sp & 255u) == 0u) { if (xb_ld(&(bar)[XB_TMO])) break; if (_sp > XB_SPIN_CAP) { atomicAdd(&(bar)[XB_TMO], 1u); break; } } } } while (0)
; __device__ __forceinline__ void xcd_barrier(const XcdBarrier& b, const bool xb_is_leader) {
;     ...
;             if (og + 1u == (tg + 1u) * nx) xb_add(&bar[XB_TOPGEN], 1u);
;             else XB_SPIN(xb_ld(&bar[XB_TOPGEN]) == tg, bar);
;             __builtin_amdgcn_fence(__ATOMIC_ACQUIRE, "agent");
;             xb_add(&bar[XB_XGEN(b.x)], 1u);
;             asm volatile("s_waitcnt vmcnt(0)" ::: "memory");
.LBB0_1807:
	s_or_b64 exec, exec, s[0:1]
	s_mov_b64 s[0:1], exec
	v_mbcnt_lo_u32_b32 v0, s0, 0
	v_mbcnt_hi_u32_b32 v0, s1, v0
	v_cmp_eq_u32_e32 vcc, 0, v0
	s_waitcnt vmcnt(0)
	buffer_inv sc1
	s_and_saveexec_b64 s[8:9], vcc
	s_cbranch_execz .LBB0_1809
	s_bcnt1_i32_b64 s0, s[0:1]
	v_mov_b32_e32 v0, 0x2000
	v_mov_b32_e32 v1, s0
.LBB0_1809:
	s_or_b64 exec, exec, s[8:9]
	s_waitcnt vmcnt(0)
